# adds: R6 (y = RH S^T + Y0, norm, gate) loads its per-head parameter vectors before the next-item prefetch so their waits no longer drain that prefetch
# baseline (speedup 1.0000x reference)
.LBB0_120:
	s_or_b64 exec, exec, s[0:1]
	v_and_b32_e32 v0, 0xffffffc0, v170
	v_and_b32_e32 v152, 48, v191
	v_or3_b32 v170, v0, v152, v3
	v_lshlrev_b32_e32 v152, 16, v186
	v_and_b32_e32 v153, 0xffff0000, v186
	v_lshlrev_b32_e32 v154, 16, v187
	v_and_b32_e32 v155, 0xffff0000, v187
	v_lshlrev_b32_e32 v160, 16, v184
	v_and_b32_e32 v161, 0xffff0000, v184
	v_mfma_f32_16x16x32_bf16 v[48:51], v[48:51], v[60:63], v[152:155]
	v_lshlrev_b32_e32 v162, 16, v185
	v_and_b32_e32 v163, 0xffff0000, v185
	v_lshlrev_b32_e32 v184, 16, v58
	v_and_b32_e32 v185, 0xffff0000, v58
	v_lshlrev_b32_e32 v186, 16, v59
	v_and_b32_e32 v187, 0xffff0000, v59
	v_lshlrev_b32_e32 v194, 16, v56
	v_and_b32_e32 v195, 0xffff0000, v56
	v_lshlrev_b32_e32 v196, 16, v57
	v_and_b32_e32 v197, 0xffff0000, v57
	v_mfma_f32_16x16x32_bf16 v[56:59], v[52:55], v[64:67], v[48:51]
	s_movk_i32 s0, 0x3c0
	v_and_or_b32 v0, v191, s0, v2
	v_ashrrev_i32_e32 v171, 31, v170
	v_mfma_f32_16x16x32_bf16 v[48:51], v[68:71], v[60:63], v[160:163]
	v_lshlrev_b32_e32 v71, 2, v0
	v_lshlrev_b32_e32 v68, 16, v180
	v_and_b32_e32 v69, 0xffff0000, v180
	v_mfma_f32_16x16x32_bf16 v[52:55], v[72:75], v[64:67], v[48:51]
	v_lshlrev_b32_e32 v73, 16, v182
	v_and_b32_e32 v74, 0xffff0000, v182
	v_mul_f32_e32 v68, v68, v73
	v_mfma_f32_16x16x32_bf16 v[48:51], v[76:79], v[60:63], v[184:187]
	v_add_f32_e32 v77, 0, v56
	v_lshlrev_b32_e32 v70, 16, v181
	v_lshlrev_b32_e32 v75, 16, v183
	v_mfma_f32_16x16x32_bf16 v[60:63], v[84:87], v[60:63], v[194:197]
	v_and_b32_e32 v72, 0xffff0000, v181
	v_and_b32_e32 v76, 0xffff0000, v183
	v_lshlrev_b32_e32 v0, 1, v0
	v_mfma_f32_16x16x32_bf16 v[48:51], v[80:83], v[64:67], v[48:51]
	v_lshlrev_b32_e32 v80, 16, v151
	v_and_b32_e32 v81, 0xffff0000, v151
	v_lshlrev_b32_e32 v82, 16, v165
	v_mfma_f32_16x16x32_bf16 v[60:63], v[88:91], v[64:67], v[60:63]
	v_mov_b64_e32 v[64:65], v[216:217]
	v_mov_b64_e32 v[66:67], v[218:219]
	v_and_b32_e32 v83, 0xffff0000, v165
	v_lshlrev_b32_e32 v90, 16, v150
	v_and_b32_e32 v91, 0xffff0000, v150
	v_lshlrev_b32_e32 v150, 16, v164
	v_and_b32_e32 v151, 0xffff0000, v164
	v_lshlrev_b32_e32 v164, 16, v146
	v_and_b32_e32 v165, 0xffff0000, v146
	v_lshlrev_b32_e32 v146, 16, v148
	s_mov_b32 s0, 0x800000
	v_add_u32_e32 v191, s81, v191
	s_waitcnt vmcnt(9)
	v_mov_b64_e32 v[186:187], v[114:115]
	s_waitcnt vmcnt(8)
	v_mov_b64_e32 v[184:185], v[116:117]
	v_mov_b64_e32 v[180:181], v[98:99]
	v_mov_b64_e32 v[182:183], v[100:101]
	v_fma_f32 v73, v68, v64, 0
	v_add_f32_e32 v64, v57, v77
	v_mul_f32_e32 v68, v69, v74
	v_fmac_f32_e32 v73, v68, v65
	v_add_f32_e32 v64, v58, v64
	v_mul_f32_e32 v65, v70, v75
	v_fmac_f32_e32 v73, v65, v66
	v_add_f32_e32 v68, v59, v64
	v_mul_f32_e32 v64, v72, v76
	v_fmac_f32_e32 v73, v64, v67
	v_mov_b64_e32 v[64:65], v[220:221]
	v_mov_b64_e32 v[66:67], v[222:223]
	v_lshlrev_b32_e32 v69, 16, v176
	v_lshlrev_b32_e32 v72, 16, v178
	v_add_f32_e32 v68, v52, v68
	v_mul_f32_e32 v69, v69, v72
	v_and_b32_e32 v70, 0xffff0000, v176
	v_and_b32_e32 v74, 0xffff0000, v178
	v_lshlrev_b32_e32 v72, 16, v174
	v_fmac_f32_e32 v73, v69, v64
	v_add_f32_e32 v64, v53, v68
	v_mul_f32_e32 v68, v70, v74
	v_add_f32_e32 v64, v54, v64
	v_fmac_f32_e32 v73, v68, v65
	v_add_f32_e32 v70, v55, v64
	v_and_b32_e32 v65, 0xffff0000, v177
	v_lshlrev_b32_e32 v64, 16, v177
	v_and_b32_e32 v69, 0xffff0000, v179
	v_lshlrev_b32_e32 v68, 16, v179
	v_pk_mul_f32 v[64:65], v[64:65], v[68:69]
	v_add_f32_e32 v68, v48, v70
	v_pk_mul_f32 v[64:65], v[64:65], v[66:67]
	v_add_f32_e32 v70, v49, v68
	v_add_f32_e32 v64, v64, v73
	v_add_f32_e32 v74, v65, v64
	v_mov_b64_e32 v[64:65], v[224:225]
	v_mov_b64_e32 v[66:67], v[226:227]
	v_and_b32_e32 v69, 0xffff0000, v172
	v_lshlrev_b32_e32 v68, 16, v172
	v_and_b32_e32 v73, 0xffff0000, v174
	v_pk_mul_f32 v[68:69], v[68:69], v[72:73]
	v_and_b32_e32 v73, 0xffff0000, v168
	v_mov_b64_e32 v[176:177], v[106:107]
	v_mov_b64_e32 v[178:179], v[108:109]
	v_pk_mul_f32 v[64:65], v[68:69], v[64:65]
	s_nop 0
	v_add_f32_e32 v64, v64, v74
	v_add_f32_e32 v72, v65, v64
	v_add_f32_e32 v64, v50, v70
	v_add_f32_e32 v70, v51, v64
	v_and_b32_e32 v65, 0xffff0000, v173
	v_lshlrev_b32_e32 v64, 16, v173
	v_and_b32_e32 v69, 0xffff0000, v175
	v_lshlrev_b32_e32 v68, 16, v175
	v_pk_mul_f32 v[64:65], v[64:65], v[68:69]
	v_add_f32_e32 v68, v60, v70
	v_pk_mul_f32 v[64:65], v[64:65], v[66:67]
	v_add_f32_e32 v70, v61, v68
	v_add_f32_e32 v64, v64, v72
	v_add_f32_e32 v74, v65, v64
	v_mov_b64_e32 v[64:65], v[228:229]
	v_mov_b64_e32 v[66:67], v[230:231]
	v_and_b32_e32 v69, 0xffff0000, v166
	v_lshlrev_b32_e32 v68, 16, v166
	v_lshlrev_b32_e32 v72, 16, v168
	v_pk_mul_f32 v[68:69], v[68:69], v[72:73]
	v_mov_b64_e32 v[172:173], v[118:119]
	v_mov_b64_e32 v[174:175], v[124:125]
	v_pk_mul_f32 v[64:65], v[68:69], v[64:65]
	s_nop 0
	v_add_f32_e32 v64, v64, v74
	v_add_f32_e32 v72, v65, v64
	v_add_f32_e32 v64, v62, v70
	v_add_f32_e32 v70, v63, v64
	v_and_b32_e32 v65, 0xffff0000, v167
	v_lshlrev_b32_e32 v64, 16, v167
	v_and_b32_e32 v69, 0xffff0000, v169
	v_lshlrev_b32_e32 v68, 16, v169
	v_pk_mul_f32 v[64:65], v[64:65], v[68:69]
	s_nop 0
	v_pk_mul_f32 v[64:65], v[64:65], v[66:67]
	s_nop 0
	v_add_f32_e32 v64, v64, v72
	v_add_f32_e32 v64, v65, v64
	ds_bpermute_b32 v65, v188, v70
	s_waitcnt lgkmcnt(0)
	v_add_f32_e32 v65, v70, v65
	ds_bpermute_b32 v66, v189, v65
	s_waitcnt lgkmcnt(0)
	v_add_f32_e32 v65, v65, v66
	ds_bpermute_b32 v66, v188, v64
	v_mul_f32_e32 v78, 0x3c800000, v65
	v_pk_add_f32 v[72:73], v[60:61], v[78:79] op_sel_hi:[1,0] neg_lo:[0,1] neg_hi:[0,1]
	v_lshlrev_b64 v[60:61], 11, v[170:171]
	v_pk_add_f32 v[68:69], v[62:63], v[78:79] op_sel_hi:[1,0] neg_lo:[0,1] neg_hi:[0,1]
	s_waitcnt lgkmcnt(0)
	v_add_f32_e32 v64, v64, v66
	ds_bpermute_b32 v66, v189, v64
	v_lshl_add_u64 v[84:85], s[34:35], 0, v[60:61]
	v_pk_add_f32 v[152:153], v[56:57], v[78:79] op_sel_hi:[1,0] neg_lo:[0,1] neg_hi:[0,1]
	v_pk_add_f32 v[86:87], v[58:59], v[78:79] op_sel_hi:[1,0] neg_lo:[0,1] neg_hi:[0,1]
	v_pk_mul_f32 v[154:155], v[152:153], v[152:153]
	s_waitcnt lgkmcnt(0)
	v_add_f32_e32 v70, v64, v66
	v_mov_b64_e32 v[60:61], v[232:233]
	v_mov_b64_e32 v[62:63], v[234:235]
	v_mov_b64_e32 v[64:65], v[236:237]
	v_mov_b64_e32 v[66:67], v[238:239]
	v_pk_mul_f32 v[88:89], v[86:87], v[86:87]
	v_lshl_add_u64 v[56:57], v[84:85], 0, v[0:1]
	v_add_f32_e32 v0, v154, v155
	v_lshlrev_b32_e32 v58, 16, v147
	v_and_b32_e32 v59, 0xffff0000, v147
	v_lshlrev_b32_e32 v84, 16, v149
	v_and_b32_e32 v85, 0xffff0000, v149
	v_and_b32_e32 v147, 0xffff0000, v148
	v_pk_add_f32 v[148:149], v[52:53], v[78:79] op_sel_hi:[1,0] neg_lo:[0,1] neg_hi:[0,1]
	v_add_f32_e32 v0, v88, v0
	v_pk_mul_f32 v[166:167], v[148:149], v[148:149]
	v_add_f32_e32 v0, v89, v0
	v_pk_add_f32 v[160:161], v[54:55], v[78:79] op_sel_hi:[1,0] neg_lo:[0,1] neg_hi:[0,1]
	v_add_f32_e32 v0, v166, v0
	v_pk_mul_f32 v[162:163], v[160:161], v[160:161]
	v_add_f32_e32 v0, v167, v0
	v_pk_add_f32 v[168:169], v[50:51], v[78:79] op_sel_hi:[1,0] neg_lo:[0,1] neg_hi:[0,1]
	v_pk_add_f32 v[78:79], v[48:49], v[78:79] op_sel_hi:[1,0] neg_lo:[0,1] neg_hi:[0,1]
	v_add_f32_e32 v0, v162, v0
	v_pk_mul_f32 v[48:49], v[78:79], v[78:79]
	v_add_f32_e32 v0, v163, v0
	v_add_f32_e32 v0, v48, v0
	v_pk_mul_f32 v[50:51], v[168:169], v[168:169]
	v_add_f32_e32 v0, v49, v0
	v_add_f32_e32 v0, v50, v0
	v_pk_mul_f32 v[74:75], v[72:73], v[72:73]
	v_add_f32_e32 v0, v51, v0
	v_add_f32_e32 v0, v74, v0
	v_pk_mul_f32 v[76:77], v[68:69], v[68:69]
	v_add_f32_e32 v0, v75, v0
	v_add_f32_e32 v0, v76, v0
	v_add_f32_e32 v0, v77, v0
	ds_bpermute_b32 v48, v188, v0
	v_lshlrev_b32_e32 v54, 16, v143
	v_and_b32_e32 v55, 0xffff0000, v143
	v_lshlrev_b32_e32 v170, 16, v142
	v_and_b32_e32 v171, 0xffff0000, v142
	s_waitcnt lgkmcnt(0)
	v_add_f32_e32 v0, v0, v48
	ds_bpermute_b32 v48, v189, v0
	v_lshlrev_b32_e32 v52, 16, v145
	v_and_b32_e32 v53, 0xffff0000, v145
	v_lshlrev_b32_e32 v142, 16, v144
	v_and_b32_e32 v143, 0xffff0000, v144
	s_waitcnt lgkmcnt(0)
	v_add_f32_e32 v0, v0, v48
	v_fmamk_f32 v0, v0, 0x3c800000, v214
	v_cmp_gt_f32_e32 vcc, s0, v0
	v_mul_f32_e32 v48, 0x4b800000, v0
	s_waitcnt vmcnt(3)
	v_mov_b64_e32 v[166:167], v[134:135]
	v_cndmask_b32_e32 v0, v0, v48, vcc
	v_rsq_f32_e32 v0, v0
	v_mov_b64_e32 v[144:145], v[132:133]
	v_mul_f32_e32 v48, 0x45800000, v0
	v_cndmask_b32_e32 v0, v0, v48, vcc
	v_pk_mul_f32 v[48:49], v[152:153], v[0:1] op_sel_hi:[1,0]
	v_pk_mul_f32 v[50:51], v[86:87], v[0:1] op_sel_hi:[1,0]
	v_pk_fma_f32 v[48:49], v[60:61], v[48:49], v[64:65]
	v_pk_fma_f32 v[50:51], v[62:63], v[50:51], v[66:67]
	v_pk_fma_f32 v[48:49], v[70:71], v[90:91], v[48:49] op_sel_hi:[0,1,1]
	v_pk_fma_f32 v[50:51], v[70:71], v[80:81], v[50:51] op_sel_hi:[0,1,1]
	v_pk_mul_f32 v[48:49], v[48:49], v[150:151]
	v_pk_mul_f32 v[50:51], v[50:51], v[82:83]
	v_cvt_pk_bf16_f32 v48, v48, v49
	v_cvt_pk_bf16_f32 v49, v50, v51
	global_store_dwordx2 v[56:57], v[48:49], off
	v_mov_b64_e32 v[48:49], v[240:241]
	v_mov_b64_e32 v[50:51], v[242:243]
	s_nop 0
	v_mov_b64_e32 v[60:61], v[244:245]
	v_mov_b64_e32 v[62:63], v[246:247]
	v_pk_mul_f32 v[64:65], v[148:149], v[0:1] op_sel_hi:[1,0]
	v_mov_b64_e32 v[82:83], v[38:39]
	v_mov_b64_e32 v[90:91], v[46:47]
	v_mov_b64_e32 v[80:81], v[36:37]
	v_mov_b64_e32 v[88:89], v[44:45]
	v_mov_b64_e32 v[150:151], v[102:103]
	v_mov_b64_e32 v[148:149], v[112:113]
	v_pk_fma_f32 v[48:49], v[48:49], v[64:65], v[60:61]
	v_pk_mul_f32 v[60:61], v[160:161], v[0:1] op_sel_hi:[1,0]
	v_pk_fma_f32 v[48:49], v[70:71], v[164:165], v[48:49] op_sel_hi:[0,1,1]
	v_pk_fma_f32 v[50:51], v[50:51], v[60:61], v[62:63]
	v_pk_mul_f32 v[48:49], v[48:49], v[146:147]
	v_pk_fma_f32 v[50:51], v[70:71], v[58:59], v[50:51] op_sel_hi:[0,1,1]
	v_pk_mul_f32 v[50:51], v[50:51], v[84:85]
	v_cvt_pk_bf16_f32 v48, v48, v49
	v_cvt_pk_bf16_f32 v49, v50, v51
	global_store_dwordx2 v[56:57], v[48:49], off offset:32
	global_load_dwordx4 v[48:51], v71, s[38:39] offset:128
	s_nop 0
	global_load_dwordx4 v[58:61], v71, s[40:41] offset:128
	v_pk_mul_f32 v[62:63], v[78:79], v[0:1] op_sel_hi:[1,0]
	v_mov_b64_e32 v[66:67], v[14:15]
	v_mov_b64_e32 v[78:79], v[34:35]
	v_mov_b64_e32 v[86:87], v[42:43]
	v_mov_b64_e32 v[64:65], v[12:13]
	v_mov_b64_e32 v[76:77], v[32:33]
	v_mov_b64_e32 v[84:85], v[40:41]
	v_mov_b64_e32 v[146:147], v[110:111]
	v_mov_b64_e32 v[164:165], v[104:105]
	s_waitcnt vmcnt(0)
	v_pk_fma_f32 v[48:49], v[48:49], v[62:63], v[58:59]
	v_pk_mul_f32 v[58:59], v[168:169], v[0:1] op_sel_hi:[1,0]
	v_pk_fma_f32 v[48:49], v[70:71], v[170:171], v[48:49] op_sel_hi:[0,1,1]
	v_pk_fma_f32 v[50:51], v[50:51], v[58:59], v[60:61]
	v_pk_mul_f32 v[48:49], v[48:49], v[142:143]
	v_pk_fma_f32 v[50:51], v[70:71], v[54:55], v[50:51] op_sel_hi:[0,1,1]
	v_pk_mul_f32 v[50:51], v[50:51], v[52:53]
	v_cvt_pk_bf16_f32 v48, v48, v49
	v_cvt_pk_bf16_f32 v49, v50, v51
	global_store_dwordx2 v[56:57], v[48:49], off offset:64
	global_load_dwordx4 v[48:51], v71, s[38:39] offset:192
	s_nop 0
	global_load_dwordx4 v[52:55], v71, s[40:41] offset:192
	v_pk_mul_f32 v[62:63], v[72:73], v[0:1] op_sel_hi:[1,0]
	v_lshlrev_b32_e32 v58, 16, v126
	v_and_b32_e32 v59, 0xffff0000, v126
	v_lshlrev_b32_e32 v60, 16, v130
	v_and_b32_e32 v61, 0xffff0000, v130
	v_mov_b64_e32 v[74:75], v[30:31]
	v_mov_b64_e32 v[72:73], v[28:29]
	v_mov_b64_e32 v[168:169], v[136:137]
	v_mov_b64_e32 v[142:143], v[128:129]
	v_mov_b32_e32 v170, v192
	s_waitcnt vmcnt(0)
	v_pk_fma_f32 v[48:49], v[48:49], v[62:63], v[52:53]
	s_nop 0
	v_pk_fma_f32 v[48:49], v[70:71], v[58:59], v[48:49] op_sel_hi:[0,1,1]
	v_pk_mul_f32 v[48:49], v[48:49], v[60:61]
	v_pk_mul_f32 v[60:61], v[68:69], v[0:1] op_sel_hi:[1,0]
	v_lshlrev_b32_e32 v52, 16, v127
	v_and_b32_e32 v53, 0xffff0000, v127
	v_pk_fma_f32 v[50:51], v[50:51], v[60:61], v[54:55]
	v_lshlrev_b32_e32 v58, 16, v131
	v_and_b32_e32 v59, 0xffff0000, v131
	v_pk_fma_f32 v[50:51], v[70:71], v[52:53], v[50:51] op_sel_hi:[0,1,1]
	v_pk_mul_f32 v[50:51], v[50:51], v[58:59]
	v_cvt_pk_bf16_f32 v48, v48, v49
	v_cvt_pk_bf16_f32 v49, v50, v51
	global_store_dwordx2 v[56:57], v[48:49], off offset:96
	v_mov_b64_e32 v[62:63], v[10:11]
	v_mov_b64_e32 v[50:51], v[18:19]
	v_mov_b64_e32 v[54:55], v[22:23]
	v_mov_b64_e32 v[70:71], v[26:27]
	v_mov_b64_e32 v[60:61], v[8:9]
	v_mov_b64_e32 v[48:49], v[16:17]
	v_mov_b64_e32 v[52:53], v[20:21]
	v_mov_b64_e32 v[68:69], v[24:25]
	v_mov_b64_e32 v[58:59], v[120:121]
	v_mov_b64_e32 v[56:57], v[122:123]
	v_mov_b64_e32 v[126:127], v[138:139]
	v_mov_b64_e32 v[130:131], v[140:141]
	s_andn2_b64 exec, exec, s[44:45]
	s_cbranch_execz .LBB0_125
.LBB0_121:
	s_movk_i32 s100, 0x3c0
	v_and_or_b32 v215, v191, s100, v2
	v_lshlrev_b32_e32 v215, 2, v215
	global_load_dwordx4 v[216:219], v215, s[42:43]
	global_load_dwordx4 v[220:223], v215, s[42:43] offset:64
	global_load_dwordx4 v[224:227], v215, s[42:43] offset:128
	global_load_dwordx4 v[228:231], v215, s[42:43] offset:192
	global_load_dwordx4 v[232:235], v215, s[38:39]
	global_load_dwordx4 v[236:239], v215, s[40:41]
	global_load_dwordx4 v[240:243], v215, s[38:39] offset:64
	global_load_dwordx4 v[244:247], v215, s[40:41] offset:64
	v_readlane_b32 s0, v253, 44
	v_readlane_b32 s1, v253, 45
	s_nop 0
	v_add_u32_e32 v192, s0, v170
	s_movk_i32 s0, 0x4000
	v_cmp_gt_i32_e32 vcc, s0, v192
	s_movk_i32 s0, 0x3fff
	v_cmp_lt_i32_e64 s[0:1], s0, v192
	s_or_b64 s[44:45], s[0:1], s[44:45]
	s_and_saveexec_b64 s[0:1], vcc
	s_cbranch_execz .Lr6_np
	s_movk_i32 s64, 0xffc0
	v_and_or_b32 v20, v192, s64, v190
	v_ashrrev_i32_e32 v16, 2, v192
	v_ashrrev_i32_e32 v21, 31, v20
	v_lshlrev_b64 v[24:25], 10, v[20:21]
	v_lshlrev_b32_e32 v0, 6, v16
	s_movk_i32 s64, 0x3c0
	v_and_or_b32 v0, v0, s64, v24
	v_or_b32_e32 v24, v0, v2
	v_ashrrev_i32_e32 v17, 31, v16
	v_lshlrev_b64 v[134:135], 1, v[24:25]
	v_lshlrev_b64 v[18:19], 13, v[16:17]
	v_or_b32_e32 v34, 32, v134
	v_mov_b32_e32 v35, v135
	v_lshl_add_u64 v[12:13], v[92:93], 0, v[18:19]
	v_lshl_add_u64 v[32:33], v[96:97], 0, v[18:19]
	v_lshl_add_u64 v[24:25], s[6:7], 0, v[134:135]
	v_lshl_add_u64 v[26:27], s[8:9], 0, v[134:135]
	v_lshl_add_u64 v[28:29], s[10:11], 0, v[134:135]
	v_lshl_add_u64 v[30:31], s[30:31], 0, v[134:135]
	v_lshl_add_u64 v[36:37], s[6:7], 0, v[34:35]
	v_lshl_add_u64 v[42:43], s[10:11], 0, v[34:35]
	s_movk_i32 s64, 0x1000
	global_load_dwordx4 v[8:11], v[12:13], off
	s_nop 0
	global_load_dwordx4 v[12:15], v[12:13], off offset:1024
	v_lshl_add_u64 v[40:41], v[94:95], 0, v[18:19]
	global_load_dwordx4 v[16:19], v[32:33], off
	global_load_dwordx4 v[20:23], v[32:33], off offset:1024
	global_load_dwordx2 v[98:99], v[24:25], off
	global_load_dwordx2 v[100:101], v[26:27], off
	global_load_dwordx2 v[102:103], v[28:29], off
	global_load_dwordx2 v[104:105], v[30:31], off
	s_nop 0
	global_load_dwordx4 v[24:27], v[32:33], off offset:2048
	global_load_dwordx4 v[28:31], v[32:33], off offset:3072
	v_lshl_add_u64 v[38:39], s[8:9], 0, v[34:35]
	v_lshl_add_u64 v[34:35], s[30:31], 0, v[34:35]
	global_load_dwordx2 v[106:107], v[36:37], off
	global_load_dwordx2 v[108:109], v[38:39], off
	global_load_dwordx2 v[110:111], v[42:43], off
	global_load_dwordx2 v[112:113], v[34:35], off
	v_add_co_u32_e32 v44, vcc, s64, v32
	v_or_b32_e32 v42, 64, v134
	v_mov_b32_e32 v43, v135
	v_addc_co_u32_e32 v45, vcc, 0, v33, vcc
	v_lshl_add_u64 v[46:47], s[6:7], 0, v[42:43]
	v_lshl_add_u64 v[114:115], s[8:9], 0, v[42:43]
	v_lshl_add_u64 v[116:117], s[10:11], 0, v[42:43]
	v_lshl_add_u64 v[42:43], s[30:31], 0, v[42:43]
	global_load_dwordx4 v[32:35], v[44:45], off
	global_load_dwordx4 v[36:39], v[44:45], off offset:1024
	global_load_dwordx2 v[118:119], v[46:47], off
	global_load_dwordx2 v[124:125], v[114:115], off
	global_load_dwordx2 v[128:129], v[116:117], off
	global_load_dwordx2 v[132:133], v[42:43], off
	s_nop 0
	global_load_dwordx2 v[114:115], v[40:41], off
	global_load_dwordx2 v[116:117], v[40:41], off offset:512
	global_load_dwordx2 v[120:121], v[40:41], off offset:1024
	global_load_dwordx2 v[122:123], v[40:41], off offset:1536
	s_nop 0
	global_load_dwordx4 v[40:43], v[44:45], off offset:2048
	s_nop 0
	global_load_dwordx4 v[44:47], v[44:45], off offset:3072
	v_or_b32_e32 v134, 0x60, v134
	v_lshl_add_u64 v[136:137], s[6:7], 0, v[134:135]
	v_lshl_add_u64 v[138:139], s[8:9], 0, v[134:135]
	v_lshl_add_u64 v[140:141], s[10:11], 0, v[134:135]
	v_lshl_add_u64 v[152:153], s[30:31], 0, v[134:135]
	global_load_dwordx2 v[134:135], v[136:137], off
	s_nop 0
	global_load_dwordx2 v[136:137], v[138:139], off
	s_nop 0
	global_load_dwordx2 v[138:139], v[140:141], off
	s_nop 0
	global_load_dwordx2 v[140:141], v[152:153], off
	s_waitcnt vmcnt(30)
	s_branch .LBB0_120
.Lr6_np:
	s_waitcnt vmcnt(0)
	s_branch .LBB0_120
